# also moved ab_out, cd_in, cd_out, w_uq, w_ukv weight conversions from phase 0 to the idle half of the grid in phase 7
# speedup vs baseline: 1.0121x; 1.0038x over previous
; #define LAS __attribute__((address_space(3)))
; __device__ __forceinline__ void conv_matrix(const float* W, int K, int N, const float* gain, bf16_t* WT, int Kd, int mode, int row_off, LAS float* scr, int lane, int gw, int NGW) {
;     const int nblk = N / 32, items = nblk * (K / 64);
;     for (int it = gw; it < items; it += NGW) {
;         const int kb = it / nblk, nb = it % nblk, k0 = 64 * kb, n0 = 32 * nb;
;         float wv[32];
; #pragma unroll
;         for (int i = 0; i < 32; ++i) wv[i] = W[(size_t)(k0 + 2 * i + (lane >> 5)) * N + n0 + (lane & 31)];
; __global__ void __launch_bounds__(NTHREADS, 2) hybrid_fwd(Params P) {
;     ...
;             conv_matrix(PL->in[I_ABOUT], DM, DM, nullptr, (bf16_t*)(ws + WS_WABOUT), DM, 0, 0, scr, lane, gw, NGW);
.LBB0_106:
	s_cmpk_lt_i32 s4, 0x800
	s_cselect_b64 s[16:17], -1, 0
	s_cmpk_gt_i32 s4, 0x7ff
	s_cbranch_scc1 .LBB0_109
	v_readlane_b32 s9, v254, 10
	v_lshlrev_b32_e32 v4, 2, v54
	s_waitcnt lgkmcnt(0)
	v_mov_b32_e32 v5, v0
	v_mov_b32_e32 v2, s9
	ds_read_b64 v[2:3], v2
	v_and_b32_e32 v4, 0x7c, v4
	v_add_u32_e32 v9, s5, v4
	v_lshrrev_b32_e32 v7, 3, v1
	v_lshrrev_b32_e32 v6, 5, v1
	s_waitcnt lgkmcnt(0)
	v_lshl_add_u64 v[2:3], v[2:3], 0, v[4:5]
	v_lshlrev_b32_e32 v4, 3, v1
	v_and_b32_e32 v4, 56, v4
	v_mul_u32_u24_e32 v8, 0x84, v4
	v_lshlrev_b32_e32 v4, 1, v4
	v_lshlrev_b32_e32 v10, 2, v7
	v_lshl_add_u64 v[4:5], s[0:1], 0, v[4:5]
	s_mov_b64 s[18:19], 0xad00000
	v_add3_u32 v8, s5, v8, v10
	v_mul_u32_u24_e32 v10, 0x84, v6
	v_lshl_add_u64 v[4:5], v[4:5], 0, s[18:19]
	s_lshl_b32 s9, s4, 5
	s_lshl_b32 s12, s8, 5
	v_add_u32_e32 v9, v9, v10
	s_mov_b32 s22, s4
	s_cmp_eq_u32 s58, 0
	s_cbranch_scc1 .Lskip_c1

; #define LAS __attribute__((address_space(3)))
; __device__ __forceinline__ void conv_matrix(const float* W, int K, int N, const float* gain, bf16_t* WT, int Kd, int mode, int row_off, LAS float* scr, int lane, int gw, int NGW) {
;     const int nblk = N / 32, items = nblk * (K / 64);
;     for (int it = gw; it < items; it += NGW) {
;         const int kb = it / nblk, nb = it % nblk, k0 = 64 * kb, n0 = 32 * nb;
;         float wv[32];
; #pragma unroll
;         for (int i = 0; i < 32; ++i) wv[i] = W[(size_t)(k0 + 2 * i + (lane >> 5)) * N + n0 + (lane & 31)];
; __global__ void __launch_bounds__(NTHREADS, 2) hybrid_fwd(Params P) {
;     ...
;             conv_matrix(PL->in[I_CDIN], DM, CDN, PL->in[I_MIXN] + DM, (bf16_t*)(ws + WS_WCDIN), DM, 0, 0, scr, lane, gw, NGW);
.Lskip_c1:
.LBB0_109:
	s_cmpk_gt_i32 s4, 0xf1f
	s_cbranch_scc1 .LBB0_112
	v_readlane_b32 s9, v254, 8
	v_lshlrev_b32_e32 v6, 2, v54
	v_and_b32_e32 v6, 0x7c, v6
	s_waitcnt lgkmcnt(0)
	v_mov_b32_e32 v2, s9
	v_readlane_b32 s9, v254, 11
	ds_read_b64 v[2:3], v2
	v_mov_b32_e32 v7, v0
	v_mov_b32_e32 v4, s9
	ds_read_b64 v[4:5], v4
	v_add_u32_e32 v8, s5, v6
	s_waitcnt vmcnt(0)
	v_lshrrev_b32_e32 v17, 3, v1
	v_lshrrev_b32_e32 v16, 5, v1
	s_mov_b64 s[18:19], 0x2000
	s_waitcnt lgkmcnt(0)
	v_lshl_add_u64 v[4:5], v[4:5], 0, v[6:7]
	v_lshlrev_b32_e32 v6, 3, v1
	v_and_b32_e32 v6, 56, v6
	v_mul_u32_u24_e32 v9, 0x84, v6
	v_lshlrev_b32_e32 v6, 1, v6
	v_lshlrev_b32_e32 v10, 2, v17
	v_lshl_add_u64 v[2:3], v[2:3], 0, s[18:19]
	v_lshl_add_u64 v[6:7], s[0:1], 0, v[6:7]
	s_mov_b64 s[18:19], 0xb500000
	v_add3_u32 v18, s5, v9, v10
	v_mul_u32_u24_e32 v9, 0x84, v16
	v_lshl_add_u64 v[6:7], v[6:7], 0, s[18:19]
	s_lshl_b32 s9, s4, 5
	s_lshl_b32 s12, s8, 5
	v_add_u32_e32 v19, v8, v9
	s_mov_b32 s18, s4
	s_cmp_eq_u32 s58, 0
	s_cbranch_scc1 .Lskip_c2

; #define LAS __attribute__((address_space(3)))
; __device__ __forceinline__ void conv_matrix(const float* W, int K, int N, const float* gain, bf16_t* WT, int Kd, int mode, int row_off, LAS float* scr, int lane, int gw, int NGW) {
;     const int nblk = N / 32, items = nblk * (K / 64);
;     for (int it = gw; it < items; it += NGW) {
;         const int kb = it / nblk, nb = it % nblk, k0 = 64 * kb, n0 = 32 * nb;
;         float wv[32];
; #pragma unroll
;         for (int i = 0; i < 32; ++i) wv[i] = W[(size_t)(k0 + 2 * i + (lane >> 5)) * N + n0 + (lane & 31)];
; __global__ void __launch_bounds__(NTHREADS, 2) hybrid_fwd(Params P) {
;     ...
;             conv_matrix(PL->in[I_CDOUT], DM, DM, nullptr, (bf16_t*)(ws + WS_WCDOUT), DM, 0, 0, scr, lane, gw, NGW);
.Lskip_c2:
.LBB0_112:
	s_waitcnt lgkmcnt(0)
	v_cndmask_b32_e64 v2, 0, 1, s[16:17]
	v_cmp_ne_u32_e64 s[38:39], 1, v2
	s_andn2_b64 vcc, exec, s[16:17]
	s_cbranch_vccnz .LBB0_115
	v_readlane_b32 s9, v254, 12
	v_lshlrev_b32_e32 v4, 2, v54
	v_mov_b32_e32 v5, v0
	v_mov_b32_e32 v2, s9
	ds_read_b64 v[2:3], v2
	v_and_b32_e32 v4, 0x7c, v4
	v_add_u32_e32 v9, s5, v4
	v_lshrrev_b32_e32 v7, 3, v1
	v_lshrrev_b32_e32 v6, 5, v1
	s_waitcnt lgkmcnt(0)
	v_lshl_add_u64 v[2:3], v[2:3], 0, v[4:5]
	v_lshlrev_b32_e32 v4, 3, v1
	v_and_b32_e32 v4, 56, v4
	v_mul_u32_u24_e32 v8, 0x84, v4
	v_lshlrev_b32_e32 v4, 1, v4
	v_lshlrev_b32_e32 v10, 2, v7
	v_lshl_add_u64 v[4:5], s[0:1], 0, v[4:5]
	s_mov_b64 s[16:17], 0xc500000
	v_add3_u32 v8, s5, v8, v10
	v_mul_u32_u24_e32 v10, 0x84, v6
	v_lshl_add_u64 v[4:5], v[4:5], 0, s[16:17]
	s_lshl_b32 s9, s4, 5
	s_lshl_b32 s12, s8, 5
	v_add_u32_e32 v9, v9, v10
	s_mov_b32 s22, s4
	s_cmp_eq_u32 s58, 0
	s_cbranch_scc1 .Lskip_c3

; #define LAS __attribute__((address_space(3)))
; __device__ __forceinline__ void conv_matrix(const float* W, int K, int N, const float* gain, bf16_t* WT, int Kd, int mode, int row_off, LAS float* scr, int lane, int gw, int NGW) {
;     const int nblk = N / 32, items = nblk * (K / 64);
;     for (int it = gw; it < items; it += NGW) {
;         const int kb = it / nblk, nb = it % nblk, k0 = 64 * kb, n0 = 32 * nb;
;         float wv[32];
; #pragma unroll
;         for (int i = 0; i < 32; ++i) wv[i] = W[(size_t)(k0 + 2 * i + (lane >> 5)) * N + n0 + (lane & 31)];
; __global__ void __launch_bounds__(NTHREADS, 2) hybrid_fwd(Params P) {
;     ...
;             conv_matrix(PL->in[I_WUQ], 512, 1536, PL->in[I_CQN], (bf16_t*)(ws + WS_WUQ), 512, 0, 0, scr, lane, gw, NGW);
.Lskip_c3:
.LBB0_115:
	s_cmpk_gt_i32 s4, 0x17f
	s_cbranch_scc1 .LBB0_120
	v_readlane_b32 s9, v254, 13
	v_lshlrev_b32_e32 v6, 2, v54
	v_and_b32_e32 v6, 0x7c, v6
	v_mov_b32_e32 v2, s9
	v_readlane_b32 s9, v254, 14
	v_mov_b32_e32 v7, v0
	v_add_u32_e32 v8, s5, v6
	v_mov_b32_e32 v4, s9
	ds_read_b64 v[2:3], v2
	ds_read_b64 v[4:5], v4
	v_lshrrev_b32_e32 v44, 3, v1
	v_lshrrev_b32_e32 v35, 5, v1
	v_lshlrev_b32_e32 v10, 2, v44
	s_mov_b64 s[16:17], 0xcd00000
	s_waitcnt lgkmcnt(0)
	v_lshl_add_u64 v[4:5], v[4:5], 0, v[6:7]
	v_lshlrev_b32_e32 v6, 3, v1
	v_and_b32_e32 v6, 56, v6
	v_mul_u32_u24_e32 v9, 0x84, v6
	v_lshlrev_b32_e32 v6, 1, v6
	v_lshl_add_u64 v[6:7], s[0:1], 0, v[6:7]
	v_add3_u32 v45, s5, v9, v10
	v_mul_u32_u24_e32 v9, 0x84, v35
	v_cmp_ne_u64_e64 s[40:41], 0, v[2:3]
	v_lshl_add_u64 v[6:7], v[6:7], 0, s[16:17]
	s_lshl_b32 s9, s4, 5
	s_lshl_b32 s12, s8, 5
	v_add_u32_e32 v46, v8, v9
	s_mov_b32 s22, s4
	s_cmp_eq_u32 s58, 0
	s_cbranch_scc1 .LBB0_120
	s_branch .LBB0_118

; #define LAS __attribute__((address_space(3)))
; __device__ __forceinline__ void conv_matrix(const float* W, int K, int N, const float* gain, bf16_t* WT, int Kd, int mode, int row_off, LAS float* scr, int lane, int gw, int NGW) {
;     const int nblk = N / 32, items = nblk * (K / 64);
;     for (int it = gw; it < items; it += NGW) {
;         const int kb = it / nblk, nb = it % nblk, k0 = 64 * kb, n0 = 32 * nb;
;         float wv[32];
; #pragma unroll
;         for (int i = 0; i < 32; ++i) wv[i] = W[(size_t)(k0 + 2 * i + (lane >> 5)) * N + n0 + (lane & 31)];
; __global__ void __launch_bounds__(NTHREADS, 2) hybrid_fwd(Params P) {
;     ...
;             conv_matrix(PL->in[I_WUKV], 256, 2048, PL->in[I_CKVN], (bf16_t*)(ws + WS_WUKV), 256, 0, 0, scr, lane, gw, NGW);
.LBB0_122:
	s_andn2_b64 vcc, exec, s[16:17]
	s_cbranch_vccnz .LBB0_127
	v_readlane_b32 s9, v254, 15
	v_mov_b32_e32 v11, v0
	v_lshrrev_b32_e32 v35, 5, v1
	v_mov_b32_e32 v2, s9
	v_readlane_b32 s9, v254, 16
	v_lshrrev_b32_e32 v52, 3, v1
	s_mov_b64 s[16:17], 0xcf00000
	v_mov_b32_e32 v3, s9
	ds_read_b64 v[6:7], v2
	ds_read_b64 v[4:5], v3
	v_and_b32_e32 v2, 31, v54
	v_lshlrev_b32_e32 v10, 2, v2
	v_add_u32_e32 v12, s5, v10
	v_lshlrev_b32_e32 v13, 2, v52
	s_waitcnt lgkmcnt(0)
	v_lshl_add_u64 v[8:9], v[4:5], 0, v[10:11]
	v_lshlrev_b32_e32 v4, 3, v1
	v_and_b32_e32 v4, 56, v4
	v_lshlrev_b32_e32 v10, 1, v4
	v_mul_u32_u24_e32 v48, 0x84, v4
	v_lshl_add_u64 v[10:11], s[0:1], 0, v[10:11]
	v_mul_u32_u24_e32 v49, 0x84, v35
	v_mov_b32_e32 v3, v0
	v_cmp_ne_u64_e64 s[40:41], 0, v[6:7]
	v_mov_b32_e32 v5, v0
	v_lshl_add_u64 v[10:11], v[10:11], 0, s[16:17]
	v_add3_u32 v50, s5, v48, v13
	v_or_b32_e32 v53, 8, v52
	v_or_b32_e32 v55, 16, v52
	v_or_b32_e32 v56, 24, v52
	s_lshl_b32 s9, s4, 5
	s_lshl_b32 s12, s8, 5
	v_add_u32_e32 v51, v12, v49
	s_mov_b32 s18, s4
	s_cmp_eq_u32 s58, 0
	s_cbranch_scc1 .LBB0_127
	s_branch .LBB0_125

; #define LAS __attribute__((address_space(3)))
; __device__ __forceinline__ void conv_matrix(const float* W, int K, int N, const float* gain, bf16_t* WT, int Kd, int mode, int row_off, LAS float* scr, int lane, int gw, int NGW) {
;     const int nblk = N / 32, items = nblk * (K / 64);
;     for (int it = gw; it < items; it += NGW) {
;         const int kb = it / nblk, nb = it % nblk, k0 = 64 * kb, n0 = 32 * nb;
;         float wv[32];
; #pragma unroll
;         for (int i = 0; i < 32; ++i) wv[i] = W[(size_t)(k0 + 2 * i + (lane >> 5)) * N + n0 + (lane & 31)];
; __global__ void __launch_bounds__(NTHREADS, 2) hybrid_fwd(Params P) {
;     ...
;             for (int l2 = 0; l2 < 2; ++l2) {
;                 conv_matrix(PL->in[I_MXWQ] + (size_t)l2 * DM * 512, DM, 512, PL->in[I_MXN] + l2 * DM, (bf16_t*)(ws + WS_WMQ) + (size_t)l2 * 512 * DM, DM, 0, 0, scr, lane, gw, NGW);
;                 conv_matrix(PL->in[I_MXWO] + (size_t)l2 * 512 * DM, 512, DM, nullptr, (bf16_t*)(ws + WS_WMO) + (size_t)l2 * DM * 512, 512, 0, 0, scr, lane, gw, NGW);
.LBB0_127:
	s_cmp_eq_u32 s58, 7
	s_cbranch_scc1 .Lconv_return
	v_lshl_add_u64 v[4:5], v[4:5], 1, s[0:1]
	s_mov_b64 s[18:19], 0xd000000
	s_cmpk_lt_i32 s4, 0x200
	v_lshlrev_b32_e32 v8, 2, v2
	v_add_u32_e32 v9, s5, v48
	v_lshl_add_u64 v[6:7], v[4:5], 0, s[18:19]
	s_mov_b64 s[18:19], 0xd400000
	s_cselect_b64 s[16:17], -1, 0
	v_lshl_add_u32 v57, v52, 2, v9
	v_add3_u32 v58, s5, v8, v49
	v_lshl_add_u32 v59, v53, 2, v9
	v_lshl_add_u32 v60, v55, 2, v9
	v_lshl_add_u32 v61, v56, 2, v9
	v_lshl_add_u64 v[8:9], v[4:5], 0, s[18:19]
	s_mov_b32 s5, 0
	s_mov_b64 s[18:19], -1
	s_branch .LBB0_129

; #define LAS __attribute__((address_space(3)))
; __global__ void __launch_bounds__(NTHREADS, 2) hybrid_fwd(Params P) {
;     ...
;                 const int gw2 = (bx - nscan) * 8 + wave, NGW2 = (G - nscan) * 8;
;                 conv_ffn(PL, 1, 0, (LAS float*)(lds + wave * 16384), lane, gw2, NGW2);
;                 conv_ffn(PL, 1, 1, (LAS float*)(lds + wave * 16384), lane, gw2, NGW2);
.LBB0_734:
	v_mov_b32_e32 v54, v236
	s_lshr_b32 s10, s56, 1
	s_sub_i32 s12, s73, s10
	s_sub_i32 s10, s56, s10
	v_readfirstlane_b32 s22, v54
	s_mov_b64 s[0:1], s[30:31]
	s_movk_i32 s3, 0x5800
	s_movk_i32 s89, 0x3c80
	s_movk_i32 s91, 0x1800
	s_branch .Lconv_entry
